# seam 0: cooperative-groups barrier word kept, but one write-back + one invalidate by wave 0 and two workgroup barriers (was 2 wbl2 + 2 inv + 3 barriers + dependent loads)
# baseline (speedup 1.0000x reference)
.LBB0_92:
	s_cmp_gt_i32 s55, 1
	s_cselect_b64 s[0:1], -1, 0
	s_and_b64 s[4:5], s[4:5], s[0:1]
	s_andn2_b64 vcc, exec, s[4:5]
	s_cbranch_vccnz .LBB0_108
	s_load_dwordx2 s[18:19], s[58:59], 0x58
	s_waitcnt vmcnt(0) lgkmcnt(0)
	s_barrier
	v_readfirstlane_b32 s98, v162
	s_nop 3
	s_cmp_lt_u32 s98, 64
	s_cbranch_scc0 .Lsm0_wait
	buffer_wbl2 sc1
	s_mov_b64 vcc, exec
	s_mov_b64 exec, 1
	v_mov_b32_e32 v254, 0
	global_load_dword v255, v254, s[18:19] offset:40
	s_waitcnt vmcnt(0)
	v_readfirstlane_b32 s99, v255
	v_mov_b32_e32 v255, 1
	global_atomic_add v255, v254, v255, s[18:19] offset:32 sc0
	s_waitcnt vmcnt(0)
	v_readfirstlane_b32 s100, v255
	s_nop 3
	s_and_b32 s101, s100, 0xffff
	s_add_u32 s98, s99, -1
	s_cmp_eq_u32 s101, s98
	s_cbranch_scc0 .Lsm0_nl
	s_sub_u32 s98, 0x10000, s99
	v_mov_b32_e32 v255, s98
	global_atomic_add v254, v255, s[18:19] offset:32
.Lsm0_nl:
	s_and_b32 s100, s100, 0xffff0000
	s_mov_b32 s101, 0
.Lsm0_poll:
	global_load_dword v255, v254, s[18:19] offset:32 sc1
	s_waitcnt vmcnt(0)
	v_readfirstlane_b32 s98, v255
	s_nop 3
	s_and_b32 s98, s98, 0xffff0000
	s_cmp_lg_u32 s98, s100
	s_cbranch_scc1 .Lsm0_done
	s_add_u32 s101, s101, 1
	s_cmp_lt_u32 s101, 0x4000
	s_cbranch_scc0 .Lsm0_done
	s_sleep 1
	s_branch .Lsm0_poll
